# strategy 8 completed in the window loop: counted lgkmcnt(7/3/2) before the later S=K.Q MFMA groups
# baseline (speedup 1.0000x reference)
; __device__ __forceinline__ f32x4 mfma16(bf16x8 a, bf16x8 b, f32x4 c) { return __builtin_amdgcn_mfma_f32_16x16x32_bf16(a, b, c, 0, 0, 0); }
; __device__ __forceinline__ void tile_dma(unsigned char* lds, int slot, const bf16_t* Kg, const bf16_t* Vtg, int kb, int tid) {
;     unsigned char* kd = lds + slot * RING_SLOT; unsigned char* vd = kd + RING_V;
; #pragma unroll
;     for (int i = 0; i < 2; ++i) {
;         const int q = i * 512 + tid;
;         { const int rs = q >> 4, pos = q & 15, c = pos ^ (rs & 15), nt = rs >> 4, r16 = rs & 15;
;           const int keyl = 32 * (nt >> 1) + 8 * (r16 >> 2) + 4 * (nt & 1) + (r16 & 3);
;           __builtin_amdgcn_global_load_lds((const unsigned*)(Kg + ((size_t)kb * 64 + keyl) * 128 + c * 8),
;                                            (__attribute__((address_space(3))) unsigned*)(kd + q * 16), 16, 0, 0); }
;         { const int d = q >> 3, pos = q & 7, c = pos ^ ((d >> 1) & 7);
;           __builtin_amdgcn_global_load_lds((const unsigned*)(Vtg + (size_t)d * SEQ + kb * 64 + c * 8),
;                                            (__attribute__((address_space(3))) unsigned*)(vd + q * 16), 16, 0, 0); }
;     }
; template <int MODE>
; __device__ __forceinline__ void attn_compute(const bf16x8 (&qf)[4], const unsigned char* Ks, const unsigned char* Vs, int kb, int tok,
;                                              unsigned long long msk, f32x4 (&O)[8], float& mrow, float& lrow) {
;     ...
;         bf16x8 kf[16];
; #pragma unroll
;         for (int i = 0; i < 16; ++i) kf[i] = *(const bf16x8*)(Ks + ((i >> 2) * 16 + fr) * 256 + ((((i & 3) * 4 + fq) ^ fr) * 16));
;         __builtin_amdgcn_sched_barrier(0);
; #pragma unroll
;         for (int nt = 0; nt < 4; ++nt) {
;             S[nt] = zero4();
; #pragma unroll
;             for (int ks = 0; ks < 4; ++ks) S[nt] = mfma16(kf[nt * 4 + ks], qf[ks], S[nt]);
;         }
;     }
;     bf16x8 vf[16];
; #pragma unroll
;     for (int i = 0; i < 16; ++i) vf[i] = *(const bf16x8*)(Vs + ((i & 7) * 16 + fr) * 128 + ((((i >> 3) * 4 + fq) ^ ((fr >> 1) & 7)) * 16));
;     const bool rowok = (MODE == 0) ? true : (((msk >> kb) & 1ull) != 0ull);
;     const int key0 = kb * 64 + 8 * fq;
;     const int tb = __builtin_amdgcn_readfirstlane(tok - fr);
;     const bool interior = (kb * 64 + 63 <= tb) && (MODE == 1 || kb * 64 > tb + 15 - 512);
.LBB0_231:
	s_cmp_eq_u64 s[22:23], 0
	s_ff1_i32_b64 s24, s[22:23]
	s_cselect_b32 s15, s15, s24
	s_cmp_gt_i32 s39, 0
	s_cselect_b32 s24, -1, 2
	s_add_i32 s24, s24, s39
	s_lshl_b32 s24, s24, 15
	s_add_i32 s24, s24, 0
	s_lshl_b32 s92, s15, 6
	v_lshl_add_u64 v[2:3], s[92:93], 0, v[150:151]
	v_add_u32_e32 v4, s24, v145
	v_lshlrev_b64 v[2:3], 8, v[2:3]
	v_readfirstlane_b32 s25, v4
	v_add_u32_e32 v4, 0x4000, v4
	s_waitcnt vmcnt(4)
	s_barrier
	v_lshl_add_u64 v[0:1], s[92:93], 1, v[158:159]
	v_lshl_add_u64 v[2:3], v[160:161], 0, v[2:3]
	s_mov_b32 m0, s25
	v_readfirstlane_b32 s25, v4
	global_load_lds_dwordx4 v[2:3], off
	v_lshl_add_u64 v[2:3], v[0:1], 0, v[152:153]
	s_mov_b32 m0, s25
	v_add_u32_e32 v4, s24, v149
	global_load_lds_dwordx4 v[2:3], off
	v_lshl_add_u64 v[2:3], s[92:93], 0, v[154:155]
	v_lshlrev_b64 v[2:3], 8, v[2:3]
	v_readfirstlane_b32 s24, v4
	v_lshl_add_u64 v[2:3], v[162:163], 0, v[2:3]
	s_mov_b32 m0, s24
	v_lshl_add_u64 v[0:1], v[0:1], 0, v[156:157]
	global_load_lds_dwordx4 v[2:3], off
	v_add_u32_e32 v2, 0x4000, v4
	v_mov_b32_e32 v17, v224
	v_readfirstlane_b32 s24, v2
	s_mov_b32 m0, s24
	s_lshl_b32 s24, s39, 15
	global_load_lds_dwordx4 v[0:1], off
	s_add_i32 s24, s24, 0
	v_and_b32_e32 v30, 15, v17
	v_lshrrev_b32_e32 v31, 4, v17
	v_bfe_u32 v16, v17, 4, 2
	v_bitop3_b32 v0, v31, v30, 3 bitop3:0x6c
	v_bitop3_b32 v1, v16, v30, 4 bitop3:0x36
	v_bitop3_b32 v9, v16, v30, 8 bitop3:0x36
	v_bitop3_b32 v10, v16, v30, 12 bitop3:0x36
	v_or_b32_e32 v120, 16, v30
	v_or_b32_e32 v121, 32, v30
	v_or_b32_e32 v122, 48, v30
	v_lshl_add_u32 v8, v30, 8, s24
	v_lshlrev_b32_e32 v100, 4, v0
	v_lshlrev_b32_e32 v101, 4, v1
	v_lshlrev_b32_e32 v108, 4, v9
	v_lshlrev_b32_e32 v109, 4, v10
	v_lshl_add_u32 v26, v120, 8, s24
	v_lshl_add_u32 v92, v121, 8, s24
	v_lshl_add_u32 v110, v122, 8, s24
	v_add_u32_e32 v0, v8, v100
	v_add_u32_e32 v4, v8, v101
	v_add_u32_e32 v9, v8, v108
	v_add_u32_e32 v12, v8, v109
	v_add_u32_e32 v18, v26, v100
	v_add_u32_e32 v22, v26, v101
	v_add_u32_e32 v27, v26, v108
	v_add_u32_e32 v80, v26, v109
	v_add_u32_e32 v84, v92, v100
	v_add_u32_e32 v88, v92, v101
	v_add_u32_e32 v93, v92, v108
	v_add_u32_e32 v96, v92, v109
	v_add_u32_e32 v100, v110, v100
	v_add_u32_e32 v104, v110, v101
	v_add_u32_e32 v108, v110, v108
	ds_read_b128 v[0:3], v0
	ds_read_b128 v[4:7], v4
	ds_read_b128 v[8:11], v9
	ds_read_b128 v[12:15], v12
	ds_read_b128 v[18:21], v18
	ds_read_b128 v[22:25], v22
	ds_read_b128 v[26:29], v27
	ds_read_b128 v[80:83], v80
	ds_read_b128 v[84:87], v84
	ds_read_b128 v[88:91], v88
	ds_read_b128 v[92:95], v93
	ds_read_b128 v[96:99], v96
	ds_read_b128 v[100:103], v100
	ds_read_b128 v[104:107], v104
	v_add_u32_e32 v112, v110, v109
	ds_read_b128 v[108:111], v108
	ds_read_b128 v[116:119], v112
	s_mov_b32 s25, s93
	s_mov_b32 s26, s93
	v_mov_b32_e32 v112, s25
	v_mov_b32_e32 v113, s25
	v_mov_b32_e32 v114, s25
	v_mov_b32_e32 v115, s25
	s_mov_b32 s25, s93
	v_bfe_u32 v17, v17, 1, 3
	s_waitcnt lgkmcnt(12)
	v_mfma_f32_16x16x32_bf16 v[0:3], v[0:3], v[64:67], v[112:115]
	v_mfma_f32_16x16x32_bf16 v[0:3], v[4:7], v[68:71], v[0:3]
	v_mov_b32_e32 v4, s25
	v_mov_b32_e32 v5, s25
	v_mov_b32_e32 v6, s25
	v_mfma_f32_16x16x32_bf16 v[0:3], v[8:11], v[72:75], v[0:3]
	v_mov_b32_e32 v7, s25
	v_mov_b32_e32 v8, s26
	v_mov_b32_e32 v9, s26
	v_mov_b32_e32 v10, s26
	v_mov_b32_e32 v11, s26
	s_mov_b32 s25, s93
	v_mfma_f32_16x16x32_bf16 v[0:3], v[12:15], v[76:79], v[0:3]
	s_nop 0
	v_mov_b32_e32 v12, s25
	v_mov_b32_e32 v13, s25
	v_mov_b32_e32 v14, s25
	v_mov_b32_e32 v15, s25
	s_waitcnt lgkmcnt(7)
	v_mfma_f32_16x16x32_bf16 v[8:11], v[84:87], v[64:67], v[8:11]
	s_nop 1
	v_mov_b32_e32 v173, v3
	v_mov_b32_e32 v172, v2
	v_mov_b32_e32 v170, v1
	v_mfma_f32_16x16x32_bf16 v[4:7], v[18:21], v[64:67], v[4:7]
	v_bitop3_b32 v19, v31, v17, 3 bitop3:0x6c
	v_lshl_add_u32 v18, v30, 7, s24
	v_lshlrev_b32_e32 v19, 4, v19
	s_waitcnt lgkmcnt(3)
	v_mfma_f32_16x16x32_bf16 v[12:15], v[100:103], v[64:67], v[12:15]
	v_lshl_add_u32 v21, v120, 7, s24
	v_bitop3_b32 v17, v16, v17, 4 bitop3:0x36
	v_add_u32_e32 v20, v18, v19
	v_mfma_f32_16x16x32_bf16 v[8:11], v[88:91], v[68:71], v[8:11]
	v_lshlrev_b32_e32 v17, 4, v17
	v_add_u32_e32 v18, v18, v17
	v_mov_b32_e32 v171, v0
	v_mfma_f32_16x16x32_bf16 v[4:7], v[22:25], v[68:71], v[4:7]
	v_lshl_add_u32 v23, v121, 7, s24
	v_add_u32_e32 v22, v21, v19
	v_add_u32_e32 v24, v23, v19
	s_waitcnt lgkmcnt(2)
	v_mfma_f32_16x16x32_bf16 v[12:15], v[104:107], v[68:71], v[12:15]
	v_lshl_add_u32 v25, v122, 7, s24
	v_add_u32_e32 v19, v25, v19
	s_waitcnt lgkmcnt(0)
	ds_read_b128 v[132:135], v24 offset:16384
	ds_read_b128 v[128:131], v19 offset:16384
	v_mfma_f32_16x16x32_bf16 v[8:11], v[92:95], v[72:75], v[8:11]
	ds_read_b128 v[140:143], v20 offset:16384
	ds_read_b128 v[124:127], v20 offset:24576
	ds_read_b128 v[120:123], v20 offset:26624
	ds_read_b128 v[112:115], v20 offset:28672
	v_add_u32_e32 v19, v21, v17
	s_ff1_i32_b64 s24, s[20:21]
	v_mfma_f32_16x16x32_bf16 v[4:7], v[26:29], v[72:75], v[4:7]
	s_lshl_b32 s40, s24, 6
	s_or_b32 s24, s40, 63
	v_mfma_f32_16x16x32_bf16 v[12:15], v[108:111], v[72:75], v[12:15]
	v_mfma_f32_16x16x32_bf16 v[8:11], v[96:99], v[76:79], v[8:11]
	ds_read_b128 v[136:139], v22 offset:16384
	ds_read_b128 v[96:99], v20 offset:30720
	v_add_u32_e32 v20, v23, v17
	v_add_u32_e32 v17, v25, v17
	v_mfma_f32_16x16x32_bf16 v[4:7], v[80:83], v[76:79], v[4:7]
	s_nop 2
	v_mov_b32_e32 v181, v11
	v_mov_b32_e32 v180, v10
	v_mov_b32_e32 v178, v9
	v_mfma_f32_16x16x32_bf16 v[12:15], v[116:119], v[76:79], v[12:15]
	ds_read_b128 v[100:103], v20 offset:16384
	ds_read_b128 v[104:107], v17 offset:16384
	ds_read_b128 v[108:111], v18 offset:16384
	ds_read_b128 v[92:95], v18 offset:24576
	ds_read_b128 v[80:83], v18 offset:26624
	ds_read_b128 v[84:87], v18 offset:28672
	ds_read_b128 v[116:119], v19 offset:16384
	ds_read_b128 v[88:91], v18 offset:30720
	v_sub_u32_e32 v17, v164, v30
	v_mov_b32_e32 v179, v8
	v_readfirstlane_b32 s26, v17
	s_cmp_gt_i32 s24, s26
	s_cselect_b64 s[24:25], -1, 0
	s_addk_i32 s26, 0xfe0f
	s_cmp_le_i32 s40, s26
	s_cselect_b64 s[26:27], -1, 0
	s_or_b64 s[24:25], s[24:25], s[26:27]
	s_mov_b64 s[26:27], -1
	s_and_b64 vcc, exec, s[24:25]
	v_mov_b32_e32 v185, v15
	v_mov_b32_e32 v184, v14
	v_mov_b32_e32 v183, v13
	v_mov_b32_e32 v182, v12
	v_mov_b32_e32 v177, v7
	v_mov_b32_e32 v176, v6
	v_mov_b32_e32 v175, v5
	v_mov_b32_e32 v174, v4
	s_cbranch_vccz .LBB0_233
; template <int MODE>
; __device__ __forceinline__ void attn_compute(const bf16x8 (&qf)[4], const unsigned char* Ks, const unsigned char* Vs, int kb, int tok,
;                                              unsigned long long msk, f32x4 (&O)[8], float& mrow, float& lrow) {
;     ...
;     } else {
; #pragma unroll
;         for (int nt = 0; nt < 4; ++nt)
; #pragma unroll
;             for (int c = 0; c < 4; ++c) {
;                 const int key = key0 + 32 * (nt >> 1) + 4 * (nt & 1) + c;
;                 const bool ok = rowok && (key <= tok) && (MODE == 1 || key > tok - 512);
;                 S[nt][c] = ok ? S[nt][c] : -1e30f;
;                 mx = fmaxf(mx, S[nt][c]);
;             }
;     }
	v_lshl_or_b32 v16, v16, 3, s40
	v_cmp_le_i32_e32 vcc, v16, v164
	v_cmp_gt_i32_e64 s[40:41], v16, v165
	s_and_b64 vcc, vcc, s[40:41]
	v_cndmask_b32_e32 v171, v229, v0, vcc
	v_cmp_lt_i32_e32 vcc, v16, v164
	v_cmp_ge_i32_e64 s[40:41], v16, v165
	s_and_b64 vcc, vcc, s[40:41]
	v_or_b32_e32 v18, 2, v16
	v_cndmask_b32_e32 v170, v229, v1, vcc
	v_cmp_le_i32_e32 vcc, v18, v164
	v_cmp_gt_i32_e64 s[40:41], v18, v165
	s_and_b64 vcc, vcc, s[40:41]
	v_or_b32_e32 v18, 3, v16
	v_cndmask_b32_e32 v172, v229, v2, vcc
	v_cmp_le_i32_e32 vcc, v18, v164
	v_cmp_gt_i32_e64 s[40:41], v18, v165
	s_and_b64 vcc, vcc, s[40:41]
	v_or_b32_e32 v18, 4, v16
	v_cndmask_b32_e32 v173, v229, v3, vcc
	v_cmp_le_i32_e32 vcc, v18, v164
	v_cmp_gt_i32_e64 s[40:41], v18, v165
	s_and_b64 vcc, vcc, s[40:41]
	v_or_b32_e32 v18, 5, v16
	v_cndmask_b32_e32 v174, v229, v4, vcc
	v_cmp_le_i32_e32 vcc, v18, v164
	v_cmp_gt_i32_e64 s[40:41], v18, v165
	s_and_b64 vcc, vcc, s[40:41]
	v_or_b32_e32 v18, 6, v16
	v_cndmask_b32_e32 v175, v229, v5, vcc
	v_cmp_le_i32_e32 vcc, v18, v164
	v_cmp_gt_i32_e64 s[40:41], v18, v165
	s_and_b64 vcc, vcc, s[40:41]
	v_or_b32_e32 v18, 7, v16
	v_cndmask_b32_e32 v176, v229, v6, vcc
	v_cmp_le_i32_e32 vcc, v18, v164
	v_cmp_gt_i32_e64 s[40:41], v18, v165
	s_and_b64 vcc, vcc, s[40:41]
	v_or_b32_e32 v18, 32, v16
	v_cndmask_b32_e32 v177, v229, v7, vcc
	v_cmp_le_i32_e32 vcc, v18, v164
	v_cmp_gt_i32_e64 s[40:41], v18, v165
	s_and_b64 vcc, vcc, s[40:41]
	v_cndmask_b32_e32 v179, v229, v8, vcc
	v_cmp_lt_i32_e32 vcc, v18, v164
	v_cmp_ge_i32_e64 s[40:41], v18, v165
	s_and_b64 vcc, vcc, s[40:41]
	v_or_b32_e32 v18, 34, v16
	v_cndmask_b32_e32 v178, v229, v9, vcc
	v_cmp_le_i32_e32 vcc, v18, v164
	v_cmp_gt_i32_e64 s[40:41], v18, v165
	s_and_b64 vcc, vcc, s[40:41]
	v_or_b32_e32 v18, 35, v16
	v_cndmask_b32_e32 v180, v229, v10, vcc
	v_cmp_le_i32_e32 vcc, v18, v164
	v_cmp_gt_i32_e64 s[40:41], v18, v165
	s_and_b64 vcc, vcc, s[40:41]
	v_or_b32_e32 v18, 36, v16
	v_cndmask_b32_e32 v181, v229, v11, vcc
	v_cmp_le_i32_e32 vcc, v18, v164
	v_cmp_gt_i32_e64 s[40:41], v18, v165
	s_mov_b32 s26, 0xf149f2ca
	s_and_b64 vcc, vcc, s[40:41]
	v_or_b32_e32 v18, 37, v16
	v_max3_f32 v17, v171, s26, v170
	v_cndmask_b32_e32 v182, v229, v12, vcc
	v_cmp_le_i32_e32 vcc, v18, v164
	v_cmp_gt_i32_e64 s[40:41], v18, v165
	v_max3_f32 v17, v17, v172, v173
	s_and_b64 vcc, vcc, s[40:41]
	v_or_b32_e32 v18, 38, v16
	v_max3_f32 v17, v17, v174, v175
	v_cndmask_b32_e32 v183, v229, v13, vcc
	v_cmp_le_i32_e32 vcc, v18, v164
	v_cmp_gt_i32_e64 s[40:41], v18, v165
	v_max3_f32 v17, v17, v176, v177
	s_and_b64 vcc, vcc, s[40:41]
	v_or_b32_e32 v16, 39, v16
	v_max3_f32 v17, v17, v179, v178
	v_cndmask_b32_e32 v184, v229, v14, vcc
	v_cmp_le_i32_e32 vcc, v16, v164
	v_cmp_gt_i32_e64 s[40:41], v16, v165
	v_max3_f32 v17, v17, v180, v181
	s_and_b64 vcc, vcc, s[40:41]
	v_max3_f32 v17, v17, v182, v183
	v_cndmask_b32_e32 v185, v229, v15, vcc
	v_max3_f32 v17, v17, v184, v185
	s_mov_b64 s[26:27], 0
